# speedup vs baseline: 1.0002x; 1.0002x over previous
; DEVI void partialSM(f32x16& p0, f32x16& p1, float& m_reg, float& mn, float& alpha) {
;     ...
;   for (int r = 0; r < 16; ++r) p0[r] = fmaf(p0[r], C, mnC);
; #pragma unroll
;   for (int r = 0; r < 16; ++r) p1[r] = fmaf(p1[r], C, mnC);
; #pragma unroll
;   for (int r = 0; r < 16; ++r) p0[r] = __builtin_amdgcn_exp2f(p0[r]);
; }
; DEVI void finishSM(f32x16& p0, f32x16& p1, float alpha, float& l_reg, bf16x8& pa0, bf16x8& pa1, bf16x8& pa2, bf16x8& pa3) {
; #pragma unroll
;   for (int r = 0; r < 16; ++r) p1[r] = __builtin_amdgcn_exp2f(p1[r]);
;   float ps = 0;
; #pragma unroll
;   for (int r = 0; r < 16; ++r) ps += p0[r];
; #pragma unroll
;   for (int r = 0; r < 16; ++r) ps += p1[r];
;   { auto rr = __builtin_amdgcn_permlane32_swap(__float_as_uint(ps), __float_as_uint(ps), false, false);
;     ps = __uint_as_float(rr[0]) + __uint_as_float(rr[1]); }
;   l_reg = l_reg * alpha + ps;
;     ...
;   PK4(p0, 0, pa0); PK4(p0, 8, pa1); PK4(p1, 0, pa2); PK4(p1, 8, pa3);
; DEVI void qkt(f32x16& p0, f32x16& p1, const char* Ks, const char* Rs, const bf16x8* qr, const char* Qrs, int r32, int hi) {
;   p0 = f32x16{}; p1 = f32x16{};
; #pragma unroll
;   for (int d0 = 0; d0 < 8; ++d0) { int cb = (d0 * 16 + hi * 8) * 2;
;     bf16x8 b0 = *reinterpret_cast<const bf16x8*>(Ks + KSWZ(r32, cb));
;     bf16x8 b1 = *reinterpret_cast<const bf16x8*>(Ks + KSWZ(32 + r32, cb));
;     p0 = __builtin_amdgcn_mfma_f32_32x32x16_bf16(b0, qr[d0], p0, 0, 0, 0);
;     p1 = __builtin_amdgcn_mfma_f32_32x32x16_bf16(b1, qr[d0], p1, 0, 0, 0); }
.LBB0_985:
	v_cndmask_b32_e64 v222, v140, v222, s[8:9]
	v_mul_f32_e32 v152, 0xbdd53b94, v222
	v_fmamk_f32 v66, v66, 0x3dd53b94, v152
	v_fmamk_f32 v67, v67, 0x3dd53b94, v152
	v_exp_f32_e32 v141, v66
	v_add_u32_e32 v66, 0x40000, v168
	v_fmamk_f32 v68, v68, 0x3dd53b94, v152
	v_exp_f32_e32 v236, v67
	v_fmamk_f32 v69, v69, 0x3dd53b94, v152
	v_exp_f32_e32 v237, v68
	v_add_u32_e32 v68, 0x60000, v168
	v_fmamk_f32 v128, v64, 0x3dd53b94, v152
	v_exp_f32_e32 v238, v69
	v_exp_f32_e32 v140, v128
	s_waitcnt lgkmcnt(0)
	s_barrier
	global_load_dwordx4 v[128:131], v66, s[36:37] offset:3072
	v_add_u32_e32 v66, 0x2000, v166
	global_load_dwordx4 v[132:135], v68, s[36:37] offset:3072
	global_load_dwordx4 v[136:139], v66, s[36:37] offset:3072
	v_fmamk_f32 v74, v74, 0x3dd53b94, v152
	v_fmamk_f32 v75, v75, 0x3dd53b94, v152
	v_exp_f32_e32 v228, v74
	v_exp_f32_e32 v229, v75
	v_fmamk_f32 v65, v65, 0x3dd53b94, v152
	v_fmamk_f32 v70, v70, 0x3dd53b94, v152
	v_fmamk_f32 v71, v71, 0x3dd53b94, v152
	v_fmamk_f32 v72, v72, 0x3dd53b94, v152
	v_fmamk_f32 v73, v73, 0x3dd53b94, v152
	v_fmamk_f32 v76, v76, 0x3dd53b94, v152
	v_fmamk_f32 v77, v77, 0x3dd53b94, v152
	v_fmamk_f32 v78, v78, 0x3dd53b94, v152
	v_fmamk_f32 v79, v79, 0x3dd53b94, v152
	v_fmamk_f32 v64, v80, 0x3dd53b94, v152
	v_fmamk_f32 v80, v81, 0x3dd53b94, v152
	v_fmamk_f32 v241, v82, 0x3dd53b94, v152
	v_fmamk_f32 v145, v83, 0x3dd53b94, v152
	v_fmamk_f32 v144, v84, 0x3dd53b94, v152
	v_fmamk_f32 v143, v85, 0x3dd53b94, v152
	v_fmamk_f32 v142, v86, 0x3dd53b94, v152
	v_fmamk_f32 v239, v87, 0x3dd53b94, v152
	v_fmamk_f32 v154, v88, 0x3dd53b94, v152
	v_fmamk_f32 v150, v89, 0x3dd53b94, v152
	v_fmamk_f32 v146, v90, 0x3dd53b94, v152
	v_fmamk_f32 v147, v91, 0x3dd53b94, v152
	v_fmamk_f32 v148, v92, 0x3dd53b94, v152
	v_exp_f32_e32 v240, v65
	v_exp_f32_e32 v234, v70
	v_exp_f32_e32 v235, v71
	v_exp_f32_e32 v232, v72
	v_exp_f32_e32 v233, v73
	v_exp_f32_e32 v230, v76
	v_exp_f32_e32 v231, v77
	v_exp_f32_e32 v153, v78
	v_exp_f32_e32 v155, v79
	v_fmamk_f32 v149, v93, 0x3dd53b94, v152
	v_fmamk_f32 v151, v94, 0x3dd53b94, v152
	v_fmac_f32_e32 v152, 0x3dd53b94, v95
	ds_read_b128 v[66:69], v187 offset:32768
	v_add_f32_e32 v65, 0, v140
	v_add_f32_e32 v65, v240, v65
	v_add_f32_e32 v81, v141, v65
	v_exp_f32_e32 v209, v64
	s_cmp_eq_u32 s4, s2
	s_cselect_b64 vcc, -1, 0
	s_waitcnt lgkmcnt(0)
	v_mfma_f32_32x32x16_bf16 v[64:79], v[66:69], v[96:99], 0
	ds_read_b128 v[82:85], v187 offset:40960
	v_add_f32_e32 v81, v236, v81
	v_add_f32_e32 v81, v237, v81
	v_add_f32_e32 v210, v238, v81
	v_exp_f32_e32 v211, v80
	s_waitcnt lgkmcnt(0)
	v_mfma_f32_32x32x16_bf16 v[80:95], v[82:85], v[96:99], 0
	ds_read_b128 v[170:173], v188 offset:32768
	v_add_f32_e32 v210, v234, v210
	v_add_f32_e32 v210, v235, v210
	v_add_f32_e32 v210, v232, v210
	v_exp_f32_e32 v212, v241
	s_waitcnt lgkmcnt(0)
	v_mfma_f32_32x32x16_bf16 v[64:79], v[170:173], v[100:103], v[64:79]
	ds_read_b128 v[170:173], v188 offset:40960
	v_add_f32_e32 v210, v233, v210
	v_add_f32_e32 v210, v228, v210
	v_add_f32_e32 v210, v229, v210
	v_exp_f32_e32 v214, v145
	s_waitcnt lgkmcnt(0)
	v_mfma_f32_32x32x16_bf16 v[80:95], v[170:173], v[100:103], v[80:95]
	ds_read_b128 v[170:173], v189 offset:32768
	v_add_f32_e32 v145, v230, v210
	v_add_f32_e32 v145, v231, v145
	v_add_f32_e32 v145, v153, v145
	v_exp_f32_e32 v210, v144
	s_waitcnt lgkmcnt(0)
	v_mfma_f32_32x32x16_bf16 v[64:79], v[170:173], v[104:107], v[64:79]
	ds_read_b128 v[170:173], v189 offset:40960
	v_add_f32_e32 v144, v155, v145
	v_add_f32_e32 v144, v209, v144
	v_add_f32_e32 v144, v211, v144
	v_exp_f32_e32 v215, v143
	s_waitcnt lgkmcnt(0)
	v_mfma_f32_32x32x16_bf16 v[80:95], v[170:173], v[104:107], v[80:95]
	ds_read_b128 v[170:173], v190 offset:32768
	v_add_f32_e32 v143, v212, v144
	v_add_f32_e32 v143, v214, v143
	v_add_f32_e32 v216, v210, v143
	v_exp_f32_e32 v217, v142
	s_waitcnt lgkmcnt(0)
	v_mfma_f32_32x32x16_bf16 v[64:79], v[170:173], v[108:111], v[64:79]
	ds_read_b128 v[142:145], v190 offset:40960
	v_add_f32_e32 v170, v215, v216
	v_cvt_pk_bf16_f32 v140, v140, v240
	v_add_f32_e32 v216, v217, v170
	v_exp_f32_e32 v218, v239
	s_waitcnt lgkmcnt(0)
	v_mfma_f32_32x32x16_bf16 v[80:95], v[142:145], v[108:111], v[80:95]
	ds_read_b128 v[170:173], v191 offset:32768
	v_cvt_pk_bf16_f32 v141, v141, v236
	v_cvt_pk_bf16_f32 v142, v237, v238
	v_add_f32_e32 v143, v218, v216
	v_exp_f32_e32 v154, v154
	s_waitcnt lgkmcnt(0)
	v_mfma_f32_32x32x16_bf16 v[64:79], v[170:173], v[112:115], v[64:79]
	ds_read_b128 v[170:173], v191 offset:40960
	v_add_f32_e32 v144, v154, v143
	v_cvt_pk_bf16_f32 v143, v234, v235
	v_permlane32_swap_b32_e32 v140, v142
	v_exp_f32_e32 v216, v150
	s_waitcnt lgkmcnt(0)
	v_mfma_f32_32x32x16_bf16 v[80:95], v[170:173], v[112:115], v[80:95]
	ds_read_b128 v[170:173], v192 offset:32768
	v_add_f32_e32 v145, v216, v144
	v_permlane32_swap_b32_e32 v141, v143
	v_cvt_pk_bf16_f32 v144, v232, v233
	v_exp_f32_e32 v219, v146
	s_waitcnt lgkmcnt(0)
	v_mfma_f32_32x32x16_bf16 v[64:79], v[170:173], v[116:119], v[64:79]
	ds_read_b128 v[170:173], v192 offset:40960
	v_add_f32_e32 v150, v219, v145
	v_cvt_pk_bf16_f32 v145, v228, v229
	v_cvt_pk_bf16_f32 v146, v230, v231
	v_exp_f32_e32 v236, v147
	s_waitcnt lgkmcnt(0)
	v_mfma_f32_32x32x16_bf16 v[80:95], v[170:173], v[116:119], v[80:95]
	ds_read_b128 v[170:173], v193 offset:32768
	v_add_f32_e32 v150, v236, v150
	v_cvt_pk_bf16_f32 v147, v153, v155
	v_permlane32_swap_b32_e32 v144, v146
	v_exp_f32_e32 v155, v148
	s_waitcnt lgkmcnt(0)
	v_mfma_f32_32x32x16_bf16 v[64:79], v[170:173], v[120:123], v[64:79]
	ds_read_b128 v[170:173], v193 offset:40960
	v_add_f32_e32 v150, v155, v150
	v_permlane32_swap_b32_e32 v145, v147
	v_cvt_pk_bf16_f32 v148, v209, v211
	v_exp_f32_e32 v209, v149
	s_waitcnt lgkmcnt(0)
; DEVI void mask_tile(f32x16& p0, f32x16& p1, bool nv16) {
; #pragma unroll
;   for (int r = 0; r < 16; ++r) { if (!(nv16 && r < 8)) p0[r] = -1e30f; p1[r] = -1e30f; }
; }
; DEVI void qkt(f32x16& p0, f32x16& p1, const char* Ks, const char* Rs, const bf16x8* qr, const char* Qrs, int r32, int hi) {
;     ...
;   for (int d0 = 0; d0 < 4; ++d0) { int cb = (d0 * 16 + hi * 8) * 2;
;     bf16x8 b0 = *reinterpret_cast<const bf16x8*>(Rs + RSWZ(r32, cb));
;     bf16x8 b1 = *reinterpret_cast<const bf16x8*>(Rs + RSWZ(32 + r32, cb));
;     bf16x8 qf = *reinterpret_cast<const bf16x8*>(Qrs + RSWZ(r32, cb));
;     p0 = __builtin_amdgcn_mfma_f32_32x32x16_bf16(b0, qf, p0, 0, 0, 0);
;     p1 = __builtin_amdgcn_mfma_f32_32x32x16_bf16(b1, qf, p1, 0, 0, 0); }
	v_mfma_f32_32x32x16_bf16 v[80:95], v[170:173], v[120:123], v[80:95]
	ds_read_b128 v[170:173], v194 offset:32768
	v_add_f32_e32 v153, v209, v150
	v_cvt_pk_bf16_f32 v149, v212, v214
	v_cvt_pk_bf16_f32 v150, v210, v215
	v_exp_f32_e32 v210, v151
	s_waitcnt lgkmcnt(0)
	v_mfma_f32_32x32x16_bf16 v[64:79], v[170:173], v[124:127], v[64:79]
	ds_read_b128 v[170:173], v194 offset:40960
	v_add_f32_e32 v153, v210, v153
	v_cvt_pk_bf16_f32 v151, v217, v218
	v_permlane32_swap_b32_e32 v148, v150
	v_exp_f32_e32 v211, v152
	s_waitcnt lgkmcnt(0)
	v_mfma_f32_32x32x16_bf16 v[80:95], v[170:173], v[124:127], v[80:95]
	ds_read_b128 v[228:231], v195
	v_add_f32_e32 v170, v211, v153
	v_mov_b32_e32 v171, v170
	v_permlane32_swap_b32_e32 v149, v151
	ds_read_b128 v[232:235], v195 offset:4096
	v_permlane32_swap_b32_e32 v170, v171
	v_cvt_pk_bf16_f32 v152, v154, v216
	v_cvt_pk_bf16_f32 v153, v219, v236
	ds_read_b128 v[236:239], v196
	s_waitcnt lgkmcnt(0)
	v_mfma_f32_32x32x16_bf16 v[64:79], v[228:231], v[236:239], v[64:79]
	ds_read_b128 v[228:231], v197
	v_mfma_f32_32x32x16_bf16 v[80:95], v[232:235], v[236:239], v[80:95]
	ds_read_b128 v[240:243], v198
	ds_read_b128 v[232:235], v202
	ds_read_b128 v[236:239], v199 offset:4096
	s_waitcnt lgkmcnt(2)
	v_mfma_f32_32x32x16_bf16 v[64:79], v[228:231], v[240:243], v[64:79]
	ds_read_b128 v[228:231], v199
	ds_read_b128 v[244:247], v200
	s_waitcnt lgkmcnt(0)
	v_mfma_f32_32x32x16_bf16 v[64:79], v[228:231], v[244:247], v[64:79]
	ds_read_b128 v[228:231], v201
	s_waitcnt lgkmcnt(0)
	v_mfma_f32_32x32x16_bf16 v[64:79], v[228:231], v[232:235], v[64:79]
	ds_read_b128 v[226:229], v197 offset:4096
	s_waitcnt lgkmcnt(0)
	v_mfma_f32_32x32x16_bf16 v[80:95], v[226:229], v[240:243], v[80:95]
	ds_read_b128 v[240:243], v201 offset:4096
	v_cvt_pk_bf16_f32 v154, v155, v209
	v_cvt_pk_bf16_f32 v155, v210, v211
	s_nop 0
	v_permlane32_swap_b32_e32 v152, v154
	v_permlane32_swap_b32_e32 v153, v155
	v_mfma_f32_32x32x16_bf16 v[80:95], v[236:239], v[244:247], v[80:95]
	s_nop 1
	v_cndmask_b32_e32 v229, v72, v208, vcc
	v_cndmask_b32_e32 v227, v76, v208, vcc
	v_cndmask_b32_e32 v228, v73, v208, vcc
	s_waitcnt lgkmcnt(0)
	v_mfma_f32_32x32x16_bf16 v[80:95], v[240:243], v[232:235], v[80:95]
	s_nop 11
	v_cndmask_b32_e32 v73, v95, v208, vcc
	v_cndmask_b32_e32 v226, v74, v208, vcc
	v_cndmask_b32_e32 v172, v79, v208, vcc
	v_cndmask_b32_e32 v173, v78, v208, vcc
	v_cndmask_b32_e32 v223, v77, v208, vcc
	v_cndmask_b32_e32 v225, v75, v208, vcc
	v_cndmask_b32_e32 v72, v94, v208, vcc
	v_cndmask_b32_e32 v75, v93, v208, vcc
	v_cndmask_b32_e32 v74, v92, v208, vcc
	v_cndmask_b32_e32 v77, v91, v208, vcc
	v_cndmask_b32_e32 v76, v90, v208, vcc
	v_cndmask_b32_e32 v79, v89, v208, vcc
	v_cndmask_b32_e32 v78, v88, v208, vcc
	s_cbranch_vccz .Lkmask_skip
	v_cndmask_b32_e32 v87, v87, v208, vcc
	v_cndmask_b32_e32 v86, v86, v208, vcc
	v_cndmask_b32_e32 v85, v85, v208, vcc
	v_cndmask_b32_e32 v84, v84, v208, vcc
	v_cndmask_b32_e32 v83, v83, v208, vcc
	v_cndmask_b32_e32 v82, v82, v208, vcc
	v_cndmask_b32_e32 v81, v81, v208, vcc
	v_cndmask_b32_e32 v80, v80, v208, vcc
; #define SBAR() __builtin_amdgcn_sched_barrier(0)
; #define SLOAD_V(k0) do { const char* vb_ = (const char*)VTh + (size_t)(k0) * 2; const char* vb2_ = vb_ + vhalf;                \
;     vs0 = *reinterpret_cast<const bf16x8*>(vb_ + vo_v); vs1 = *reinterpret_cast<const bf16x8*>(vb2_ + vo_v); } while (0)
; #define SWRITE_KR(b) do { int kc = sc * 2; *(bf16x8*)(K_lds + (b) * SHM_K + KSWZ(sr, kc)) = ks0; *(bf16x8*)(K_lds + (b) * SHM_K + KSWZ(32 + sr, kc)) = ks1; \
;     *(bf16x8*)(R_lds + (b) * SHM_R + RSWZ(rr_, rc_ * 2)) = rs0; } while (0)
; #define SWRITE_V(b) do { *(bf16x8*)(V_lds + (b) * SHM_V + RSWZ(vd, vc * 16)) = vs0; *(bf16x8*)(V_lds + (b) * SHM_V + RSWZ(vd + 64, vc * 16)) = vs1; } while (0)
; #define SWAIT() asm volatile("s_waitcnt vmcnt(0)" ::: "memory")
; #define RESC(a) do { if (__any((a) < 1.f)) { if (hi == 0) al_l[r32] = (a); asm volatile("s_waitcnt lgkmcnt(0)" ::: "memory"); \
;     _Pragma("unroll") for (int d = 0; d < 4; ++d) _Pragma("unroll") for (int r = 0; r < 16; ++r) o[d][r] *= al_l[crow(r, hi)]; } } while (0)
; DEVI void partialSM(f32x16& p0, f32x16& p1, float& m_reg, float& mn, float& alpha) {
;     ...
;   float pmax = p0[0];
; #pragma unroll
;   for (int r = 1; r < 16; ++r) pmax = fmaxf(pmax, p0[r]);
; #pragma unroll
;   for (int r = 0; r < 16; ++r) pmax = fmaxf(pmax, p1[r]);
;   { auto rr = __builtin_amdgcn_permlane32_swap(__float_as_uint(pmax), __float_as_uint(pmax), false, false);
;     pmax = fmaxf(__uint_as_float(rr[0]), __uint_as_float(rr[1])); }
;   if (__builtin_expect(__all(pmax - m_reg <= ATHR / ASCALE), 1)) { mn = m_reg; alpha = 1.f; }
;   else { mn = fmaxf(m_reg, pmax); alpha = __builtin_amdgcn_exp2f((m_reg - mn) * C); m_reg = mn; }
; DEVI void attn_item(const u16* __restrict__ Qb, const u16* __restrict__ KNh, const u16* __restrict__ VTh, int Lpad, const u16* __restrict__ KRb,
;                     const u16* __restrict__ SZb, u16* __restrict__ AOb, int NT, char* lds, const int wid_s_) {
;     ...
;     SLOAD_V((j + 2) * 64); SBAR();
;     pv_d0(o, V_lds + SHM_V, r32, hi, pa0, pa1, pa2, pa3); partialSM(pA0, pA1, m_reg, mnA, alA);
;     SWRITE_KR(1);
;     __syncthreads(); SWAIT(); SWRITE_V(1);
;     RESC(alA); __syncthreads();
.Lkmask_skip:
	global_load_dwordx4 v[90:93], v162, s[36:37] offset:3456
	global_load_dwordx4 v[156:159], v164, s[36:37] offset:3456
	ds_read_b128 v[230:233], v177 offset:16384
	ds_read_b128 v[234:237], v161 offset:16384
	ds_read_b128 v[238:241], v180 offset:16384
	v_max_f32_e32 v88, v65, v65
	v_max_f32_e32 v89, v64, v64
	s_waitcnt lgkmcnt(2)
	v_mfma_f32_32x32x16_bf16 v[16:31], v[140:143], v[230:233], v[16:31]
	ds_read_b128 v[230:233], v177 offset:20480
	v_max_f32_e32 v88, v89, v88
	v_max3_f32 v88, v88, v66, v67
	v_max3_f32 v88, v88, v68, v69
	ds_read_b128 v[242:245], v179 offset:16384
	v_max3_f32 v88, v88, v70, v71
	v_max3_f32 v88, v88, v229, v228
	s_waitcnt lgkmcnt(1)
	v_mfma_f32_32x32x16_bf16 v[48:63], v[140:143], v[230:233], v[48:63]
	ds_read_b128 v[230:233], v177 offset:24576
	v_max3_f32 v88, v88, v226, v225
	v_max3_f32 v88, v88, v227, v223
	v_max3_f32 v88, v88, v173, v172
	v_max3_f32 v88, v88, v80, v81
	v_max3_f32 v88, v88, v82, v83
	v_max3_f32 v88, v88, v84, v85
	v_mfma_f32_32x32x16_bf16 v[16:31], v[144:147], v[234:237], v[16:31]
	ds_read_b128 v[234:237], v161 offset:20480
	v_max3_f32 v88, v88, v86, v87
	v_max3_f32 v88, v88, v78, v79
	v_max3_f32 v88, v88, v76, v77
	v_max3_f32 v88, v88, v74, v75
	v_max3_f32 v88, v88, v72, v73
	v_mov_b32_e32 v89, v88
	s_waitcnt lgkmcnt(1)
	v_mfma_f32_32x32x16_bf16 v[32:47], v[140:143], v[230:233], v[32:47]
	ds_read_b128 v[230:233], v177 offset:28672
	v_permlane32_swap_b32_e32 v88, v89
	v_max_f32_e32 v89, v89, v89
	v_max_f32_e32 v88, v88, v88
	v_max_f32_e32 v88, v88, v89
	v_sub_f32_e32 v89, v88, v222
	s_waitcnt lgkmcnt(1)
	v_mfma_f32_32x32x16_bf16 v[48:63], v[144:147], v[234:237], v[48:63]
	ds_read_b128 v[234:237], v161 offset:24576
	v_cmp_ge_f32_e32 vcc, s91, v89
	v_max_f32_e32 v89, v222, v222
	v_max_f32_e32 v89, v89, v88
	v_sub_f32_e32 v88, v222, v89
	v_mul_f32_e32 v88, 0x3dd53b94, v88
	v_exp_f32_e32 v88, v88
	s_waitcnt lgkmcnt(1)
	v_mfma_f32_32x32x16_bf16 v[0:15], v[140:143], v[230:233], v[0:15]
	s_cmp_eq_u64 vcc, exec
	s_cselect_b64 s[8:9], -1, 0
	v_cndmask_b32_e64 v88, v88, 1.0, s[8:9]
	v_cmp_gt_f32_e32 vcc, 1.0, v88
	v_mfma_f32_32x32x16_bf16 v[16:31], v[148:151], v[238:241], v[16:31]
	ds_read_b128 v[238:241], v180 offset:20480
	s_waitcnt lgkmcnt(1)
	v_mfma_f32_32x32x16_bf16 v[32:47], v[144:147], v[234:237], v[32:47]
	ds_read_b128 v[234:237], v161 offset:28672
	s_waitcnt lgkmcnt(1)
	v_mfma_f32_32x32x16_bf16 v[48:63], v[148:151], v[238:241], v[48:63]
	ds_read_b128 v[238:241], v180 offset:24576
	s_waitcnt lgkmcnt(1)
	v_mfma_f32_32x32x16_bf16 v[0:15], v[144:147], v[234:237], v[0:15]
	v_mfma_f32_32x32x16_bf16 v[16:31], v[152:155], v[242:245], v[16:31]
	ds_read_b128 v[242:245], v179 offset:20480
	s_waitcnt lgkmcnt(1)
	v_mfma_f32_32x32x16_bf16 v[32:47], v[148:151], v[238:241], v[32:47]
	ds_read_b128 v[238:241], v180 offset:28672
	s_waitcnt lgkmcnt(1)
	v_mfma_f32_32x32x16_bf16 v[48:63], v[152:155], v[242:245], v[48:63]
	ds_read_b128 v[242:245], v179 offset:24576
	s_waitcnt lgkmcnt(1)
	v_mfma_f32_32x32x16_bf16 v[0:15], v[148:151], v[238:241], v[0:15]
	s_waitcnt lgkmcnt(0)
	v_mfma_f32_32x32x16_bf16 v[32:47], v[152:155], v[242:245], v[32:47]
	ds_read_b128 v[242:245], v179 offset:28672
	s_waitcnt vmcnt(2)
	ds_write_b128 v184, v[128:131] offset:49152
	ds_write_b128 v184, v[132:135] offset:57344
	ds_write_b128 v203, v[136:139]
	s_waitcnt lgkmcnt(0)
	s_barrier
	v_mfma_f32_32x32x16_bf16 v[0:15], v[152:155], v[242:245], v[0:15]
	s_waitcnt vmcnt(0)
	ds_write_b128 v185, v[90:93] offset:16384
	ds_write_b128 v185, v[156:159] offset:24576
	s_cbranch_vccz .LBB0_989
	s_and_saveexec_b64 s[14:15], s[6:7]
	ds_write_b32 v181, v88 offset:128
	s_or_b64 exec, exec, s[14:15]
	s_waitcnt lgkmcnt(0)
	v_add_u32_e32 v94, v178, v160
	ds_read_b128 v[90:93], v94 offset:224
	ds_read_b128 v[128:131], v94 offset:192
	ds_read_b128 v[132:135], v94 offset:160
	ds_read_b128 v[136:139], v94 offset:128
	s_waitcnt lgkmcnt(3)
	v_pk_mul_f32 v[28:29], v[28:29], v[90:91]
	s_waitcnt lgkmcnt(2)
	v_pk_mul_f32 v[24:25], v[24:25], v[128:129]
	s_waitcnt lgkmcnt(1)
	v_pk_mul_f32 v[20:21], v[20:21], v[132:133]
	v_pk_mul_f32 v[30:31], v[30:31], v[92:93]
	v_pk_mul_f32 v[26:27], v[26:27], v[130:131]
	v_pk_mul_f32 v[22:23], v[22:23], v[134:135]
	s_waitcnt lgkmcnt(0)
	v_pk_mul_f32 v[18:19], v[18:19], v[138:139]
	v_pk_mul_f32 v[16:17], v[16:17], v[136:137]
	v_pk_mul_f32 v[60:61], v[60:61], v[90:91]
	v_pk_mul_f32 v[56:57], v[56:57], v[128:129]
	v_pk_mul_f32 v[52:53], v[52:53], v[132:133]
	v_pk_mul_f32 v[62:63], v[62:63], v[92:93]
	v_pk_mul_f32 v[58:59], v[58:59], v[130:131]
	v_pk_mul_f32 v[54:55], v[54:55], v[134:135]
	v_pk_mul_f32 v[50:51], v[50:51], v[138:139]
	v_pk_mul_f32 v[48:49], v[48:49], v[136:137]
	v_pk_mul_f32 v[44:45], v[44:45], v[90:91]
	v_pk_mul_f32 v[40:41], v[40:41], v[128:129]
	v_pk_mul_f32 v[36:37], v[36:37], v[132:133]
	v_pk_mul_f32 v[46:47], v[46:47], v[92:93]
	v_pk_mul_f32 v[42:43], v[42:43], v[130:131]
	v_pk_mul_f32 v[38:39], v[38:39], v[134:135]
	v_pk_mul_f32 v[34:35], v[34:35], v[138:139]
	v_pk_mul_f32 v[32:33], v[32:33], v[136:137]
	v_pk_mul_f32 v[12:13], v[12:13], v[90:91]
	v_pk_mul_f32 v[8:9], v[8:9], v[128:129]
	v_pk_mul_f32 v[4:5], v[4:5], v[132:133]
	v_pk_mul_f32 v[14:15], v[14:15], v[92:93]
	v_pk_mul_f32 v[10:11], v[10:11], v[130:131]
	v_pk_mul_f32 v[6:7], v[6:7], v[134:135]
	v_pk_mul_f32 v[2:3], v[2:3], v[138:139]
	v_pk_mul_f32 v[0:1], v[0:1], v[136:137]
